# attention exp blocks: removed no-op s_nop pads the compiler left after empty inline-asm markers (no real hazard between plain VALU and v_exp)
# speedup vs baseline: 1.0222x; 1.0005x over previous
; DEVI float opq(float x) { asm("" : "+v"(x)); return x; }
; DEVI float fexp2(float x) { return __builtin_amdgcn_exp2f(x); }
; template <int DK, int MODE, int RBM, class SF, class FF, class POST>
; DEVI void attn_tile_body(const bf16x8 (&qf)[2][DK / 32], const char* Ks, const char* Vs, SF& sf, FF& ff, POST& post,
;                          int cur, int c0, int c1, float (&m)[2], float (&l)[2], f32x4 (&o)[5][2], int fr, int fq) {
;     ...
;         const float c = cl - m[rb];
; #pragma unroll
;         for (int kb = 0; kb < 4; ++kb)
; #pragma unroll
;           for (int j = 0; j < 4; ++j) {
;             const float e = FF::HASVEC ? opq(s[kb][rb][j] + c) : opq(fmaf(s[kb][rb][j], fsc, c));
;             s[kb][rb][j] = fexp2(e);
.LBB0_543:
	v_sub_f32_e32 v2, v108, v109
	v_add_f32_e32 v3, v146, v2
	v_add_f32_e32 v196, v82, v2
	v_exp_f32_e32 v76, v3
	v_add_f32_e32 v3, v145, v2
	v_exp_f32_e32 v145, v3
	v_add_f32_e32 v3, v93, v2
	v_exp_f32_e32 v146, v3
	v_add_f32_e32 v3, v92, v2
	v_exp_f32_e32 v147, v3
	v_add_f32_e32 v3, v94, v2
	v_exp_f32_e32 v148, v3
	v_add_f32_e32 v3, v88, v2
	v_exp_f32_e32 v149, v3
	v_add_f32_e32 v3, v89, v2
	v_exp_f32_e32 v150, v3
	v_add_f32_e32 v3, v90, v2
	v_exp_f32_e32 v152, v3
	v_add_f32_e32 v3, v95, v2
	v_exp_f32_e32 v151, v3
	v_add_f32_e32 v3, v91, v2
	v_exp_f32_e32 v153, v3
	v_add_f32_e32 v3, v85, v2
	v_exp_f32_e32 v191, v3
	v_add_f32_e32 v3, v84, v2
	v_exp_f32_e32 v192, v3
	v_add_f32_e32 v3, v86, v2
	v_exp_f32_e32 v193, v3
	v_add_f32_e32 v3, v80, v2
	v_exp_f32_e32 v194, v3
	v_add_f32_e32 v3, v81, v2
	v_exp_f32_e32 v195, v3

; DEVI float opq(float x) { asm("" : "+v"(x)); return x; }
; DEVI float fexp2(float x) { return __builtin_amdgcn_exp2f(x); }
; template <int DK, int MODE, int RBM, class SF, class FF, class POST>
; DEVI void attn_tile_body(const bf16x8 (&qf)[2][DK / 32], const char* Ks, const char* Vs, SF& sf, FF& ff, POST& post,
;                          int cur, int c0, int c1, float (&m)[2], float (&l)[2], f32x4 (&o)[5][2], int fr, int fq) {
;     ...
;         const float c = cl - m[rb];
; #pragma unroll
;         for (int kb = 0; kb < 4; ++kb)
; #pragma unroll
;           for (int j = 0; j < 4; ++j) {
;             const float e = FF::HASVEC ? opq(s[kb][rb][j] + c) : opq(fmaf(s[kb][rb][j], fsc, c));
;             s[kb][rb][j] = fexp2(e);
.LBB0_551:
	v_sub_f32_e32 v2, v110, v111
	v_add_f32_e32 v3, v78, v2
	v_add_f32_e32 v95, v62, v2
	v_exp_f32_e32 v80, v3
	v_add_f32_e32 v3, v77, v2
	v_exp_f32_e32 v81, v3
	v_add_f32_e32 v3, v73, v2
	v_exp_f32_e32 v82, v3
	v_add_f32_e32 v3, v72, v2
	v_exp_f32_e32 v83, v3
	v_add_f32_e32 v3, v74, v2
	v_exp_f32_e32 v84, v3
	v_add_f32_e32 v3, v68, v2
	v_exp_f32_e32 v85, v3
	v_add_f32_e32 v3, v69, v2
	v_exp_f32_e32 v86, v3
	v_add_f32_e32 v3, v70, v2
	v_exp_f32_e32 v88, v3
	v_add_f32_e32 v3, v75, v2
	v_exp_f32_e32 v87, v3
	v_add_f32_e32 v3, v71, v2
	v_exp_f32_e32 v89, v3
	v_add_f32_e32 v3, v65, v2
	v_exp_f32_e32 v90, v3
	v_add_f32_e32 v3, v64, v2
	v_exp_f32_e32 v91, v3
	v_add_f32_e32 v3, v66, v2
	v_exp_f32_e32 v92, v3
	v_add_f32_e32 v3, v60, v2
	v_exp_f32_e32 v93, v3
	v_add_f32_e32 v3, v61, v2
	v_exp_f32_e32 v94, v3

; DEVI float opq(float x) { asm("" : "+v"(x)); return x; }
; DEVI float fexp2(float x) { return __builtin_amdgcn_exp2f(x); }
; template <int DK, int MODE, int RBM, class SF, class FF, class POST>
; DEVI void attn_tile_body(const bf16x8 (&qf)[2][DK / 32], const char* Ks, const char* Vs, SF& sf, FF& ff, POST& post,
;                          int cur, int c0, int c1, float (&m)[2], float (&l)[2], f32x4 (&o)[5][2], int fr, int fq) {
;     ...
;         const float c = cl - m[rb];
; #pragma unroll
;         for (int kb = 0; kb < 4; ++kb)
; #pragma unroll
;           for (int j = 0; j < 4; ++j) {
;             const float e = FF::HASVEC ? opq(s[kb][rb][j] + c) : opq(fmaf(s[kb][rb][j], fsc, c));
;             s[kb][rb][j] = fexp2(e);
.LBB0_562:
	v_sub_f32_e32 v2, v108, v109
	v_add_f32_e32 v3, v145, v2
	v_add_f32_e32 v195, v82, v2
	v_exp_f32_e32 v76, v3
	v_add_f32_e32 v3, v144, v2
	v_exp_f32_e32 v144, v3
	v_add_f32_e32 v3, v93, v2
	v_exp_f32_e32 v145, v3
	v_add_f32_e32 v3, v92, v2
	v_exp_f32_e32 v146, v3
	v_add_f32_e32 v3, v94, v2
	v_exp_f32_e32 v147, v3
	v_add_f32_e32 v3, v88, v2
	v_exp_f32_e32 v148, v3
	v_add_f32_e32 v3, v89, v2
	v_exp_f32_e32 v149, v3
	v_add_f32_e32 v3, v90, v2
	v_exp_f32_e32 v151, v3
	v_add_f32_e32 v3, v95, v2
	v_exp_f32_e32 v150, v3
	v_add_f32_e32 v3, v91, v2
	v_exp_f32_e32 v152, v3
	v_add_f32_e32 v3, v85, v2
	v_exp_f32_e32 v153, v3
	v_add_f32_e32 v3, v84, v2
	v_exp_f32_e32 v191, v3
	v_add_f32_e32 v3, v86, v2
	v_exp_f32_e32 v192, v3
	v_add_f32_e32 v3, v80, v2
	v_exp_f32_e32 v193, v3
	v_add_f32_e32 v3, v81, v2
	v_exp_f32_e32 v194, v3

; DEVI float opq(float x) { asm("" : "+v"(x)); return x; }
; DEVI float fexp2(float x) { return __builtin_amdgcn_exp2f(x); }
; template <int DK, int MODE, int RBM, class SF, class FF, class POST>
; DEVI void attn_tile_body(const bf16x8 (&qf)[2][DK / 32], const char* Ks, const char* Vs, SF& sf, FF& ff, POST& post,
;                          int cur, int c0, int c1, float (&m)[2], float (&l)[2], f32x4 (&o)[5][2], int fr, int fq) {
;     ...
;         const float c = cl - m[rb];
; #pragma unroll
;         for (int kb = 0; kb < 4; ++kb)
; #pragma unroll
;           for (int j = 0; j < 4; ++j) {
;             const float e = FF::HASVEC ? opq(s[kb][rb][j] + c) : opq(fmaf(s[kb][rb][j], fsc, c));
;             s[kb][rb][j] = fexp2(e);
.LBB0_596:
	v_sub_f32_e32 v149, 0, v141
	v_fmamk_f32 v82, v82, 0x3e16c740, v149
	v_fmamk_f32 v0, v94, 0x3e16c740, v149
	v_exp_f32_e32 v146, v82
	v_fmamk_f32 v82, v83, 0x3e16c740, v149
	v_fmamk_f32 v94, v95, 0x3e16c740, v149
	v_exp_f32_e32 v147, v82
	v_fmamk_f32 v82, v84, 0x3e16c740, v149
	v_exp_f32_e32 v148, v82
	v_fmamk_f32 v82, v85, 0x3e16c740, v149
	v_exp_f32_e32 v143, v94
	v_exp_f32_e32 v151, v82
	v_fmamk_f32 v82, v86, 0x3e16c740, v149
	v_fmamk_f32 v94, v96, 0x3e16c740, v149
	v_exp_f32_e32 v150, v82
	v_fmamk_f32 v82, v87, 0x3e16c740, v149
	v_exp_f32_e32 v0, v0
	v_exp_f32_e32 v152, v82
	v_fmamk_f32 v82, v88, 0x3e16c740, v149
	v_exp_f32_e32 v144, v94
	v_exp_f32_e32 v153, v82
	v_fmamk_f32 v82, v89, 0x3e16c740, v149
	v_fmamk_f32 v94, v97, 0x3e16c740, v149
	v_exp_f32_e32 v191, v82
	v_fmamk_f32 v82, v90, 0x3e16c740, v149
	v_exp_f32_e32 v192, v82
	v_fmamk_f32 v82, v91, 0x3e16c740, v149
	v_exp_f32_e32 v145, v94
	v_exp_f32_e32 v193, v82
	v_fmamk_f32 v82, v92, 0x3e16c740, v149
	v_fmac_f32_e32 v149, 0x3e16c740, v93
	v_exp_f32_e32 v194, v82

; DEVI float opq(float x) { asm("" : "+v"(x)); return x; }
; DEVI float fexp2(float x) { return __builtin_amdgcn_exp2f(x); }
; template <int DK, int MODE, int RBM, class SF, class FF, class POST>
; DEVI void attn_tile_body(const bf16x8 (&qf)[2][DK / 32], const char* Ks, const char* Vs, SF& sf, FF& ff, POST& post,
;                          int cur, int c0, int c1, float (&m)[2], float (&l)[2], f32x4 (&o)[5][2], int fr, int fq) {
;     ...
;         const float c = cl - m[rb];
; #pragma unroll
;         for (int kb = 0; kb < 4; ++kb)
; #pragma unroll
;           for (int j = 0; j < 4; ++j) {
;             const float e = FF::HASVEC ? opq(s[kb][rb][j] + c) : opq(fmaf(s[kb][rb][j], fsc, c));
;             s[kb][rb][j] = fexp2(e);
.LBB0_604:
	v_sub_f32_e32 v91, 0, v142
	v_fmamk_f32 v66, v66, 0x3e16c740, v91
	v_fmamk_f32 v78, v78, 0x3e16c740, v91
	v_exp_f32_e32 v86, v66
	v_fmamk_f32 v66, v67, 0x3e16c740, v91
	v_exp_f32_e32 v87, v66
	v_fmamk_f32 v66, v68, 0x3e16c740, v91
	v_exp_f32_e32 v82, v78
	v_exp_f32_e32 v88, v66
	v_fmamk_f32 v66, v69, 0x3e16c740, v91
	v_fmamk_f32 v78, v79, 0x3e16c740, v91
	v_exp_f32_e32 v90, v66
	v_fmamk_f32 v66, v70, 0x3e16c740, v91
	v_exp_f32_e32 v89, v66
	v_fmamk_f32 v66, v71, 0x3e16c740, v91
	v_exp_f32_e32 v83, v78
	v_exp_f32_e32 v92, v66
	v_fmamk_f32 v66, v72, 0x3e16c740, v91
	v_fmamk_f32 v78, v80, 0x3e16c740, v91
	v_exp_f32_e32 v93, v66
	v_fmamk_f32 v66, v73, 0x3e16c740, v91
	v_exp_f32_e32 v94, v66
	v_fmamk_f32 v66, v74, 0x3e16c740, v91
	v_exp_f32_e32 v84, v78
	v_exp_f32_e32 v95, v66
	v_fmamk_f32 v66, v75, 0x3e16c740, v91
	v_fmamk_f32 v78, v81, 0x3e16c740, v91
	v_exp_f32_e32 v96, v66
	v_fmamk_f32 v66, v76, 0x3e16c740, v91
	v_fmac_f32_e32 v91, 0x3e16c740, v77
	v_exp_f32_e32 v85, v78
	v_exp_f32_e32 v97, v66

; DEVI float opq(float x) { asm("" : "+v"(x)); return x; }
; DEVI float fexp2(float x) { return __builtin_amdgcn_exp2f(x); }
; template <int DK, int MODE, int RBM, class SF, class FF, class POST>
; DEVI void attn_tile_body(const bf16x8 (&qf)[2][DK / 32], const char* Ks, const char* Vs, SF& sf, FF& ff, POST& post,
;                          int cur, int c0, int c1, float (&m)[2], float (&l)[2], f32x4 (&o)[5][2], int fr, int fq) {
;     ...
;       if (MODE == 2) {
;         const float c = cl - m[rb];
; #pragma unroll
;         for (int kb = 0; kb < 4; ++kb)
; #pragma unroll
;           for (int j = 0; j < 4; ++j) {
;             const float e = FF::HASVEC ? opq(s[kb][rb][j] + c) : opq(fmaf(s[kb][rb][j], fsc, c));
;             s[kb][rb][j] = opq(fexp2(e) * l[rb]);
;           }
.LBB0_828:
	s_andn2_saveexec_b64 s[38:39], s[54:55]
	s_cbranch_execz .LBB0_830
	v_fmamk_f32 v76, v76, 0x3e38aa3b, v199
	v_fmamk_f32 v77, v77, 0x3e38aa3b, v199
	v_fmamk_f32 v72, v72, 0x3e38aa3b, v199
	v_fmamk_f32 v73, v73, 0x3e38aa3b, v199
	v_fmamk_f32 v68, v68, 0x3e38aa3b, v199
	v_fmamk_f32 v69, v69, 0x3e38aa3b, v199
	v_exp_f32_e32 v76, v76
	v_exp_f32_e32 v77, v77
	v_exp_f32_e32 v72, v72
	v_exp_f32_e32 v73, v73
	v_exp_f32_e32 v68, v68
	v_exp_f32_e32 v69, v69
	v_fmamk_f32 v2, v80, 0x3e38aa3b, v199
	v_fmamk_f32 v3, v81, 0x3e38aa3b, v199
	v_fmamk_f32 v80, v82, 0x3e38aa3b, v199
	v_fmamk_f32 v81, v83, 0x3e38aa3b, v199
	v_mul_f32_e32 v120, v102, v76
	v_mul_f32_e32 v121, v102, v77
	v_fmamk_f32 v76, v78, 0x3e38aa3b, v199
	v_fmamk_f32 v77, v79, 0x3e38aa3b, v199
	v_mul_f32_e32 v128, v102, v72
	v_mul_f32_e32 v129, v102, v73
	v_fmamk_f32 v72, v74, 0x3e38aa3b, v199
	v_fmamk_f32 v73, v75, 0x3e38aa3b, v199
	v_mul_f32_e32 v132, v102, v68
	v_mul_f32_e32 v133, v102, v69
	v_fmamk_f32 v68, v70, 0x3e38aa3b, v199
	v_fmamk_f32 v69, v71, 0x3e38aa3b, v199
	v_exp_f32_e32 v2, v2
	v_exp_f32_e32 v3, v3
	v_exp_f32_e32 v80, v80
	v_exp_f32_e32 v81, v81
	v_exp_f32_e32 v76, v76
	v_exp_f32_e32 v77, v77
	v_exp_f32_e32 v72, v72
	v_exp_f32_e32 v73, v73
	v_exp_f32_e32 v68, v68
	v_exp_f32_e32 v69, v69
	v_mul_f32_e32 v2, v102, v2
	v_mul_f32_e32 v3, v102, v3
	v_mul_f32_e32 v118, v102, v80
	v_mul_f32_e32 v119, v102, v81
	v_mul_f32_e32 v126, v102, v76
	v_mul_f32_e32 v127, v102, v77
	v_mul_f32_e32 v130, v102, v72
	v_mul_f32_e32 v131, v102, v73
	v_mul_f32_e32 v134, v102, v68
	v_mul_f32_e32 v135, v102, v69

; DEVI float opq(float x) { asm("" : "+v"(x)); return x; }
; DEVI float fexp2(float x) { return __builtin_amdgcn_exp2f(x); }
; template <int DK, int MODE, int RBM, class SF, class FF, class POST>
; DEVI void attn_tile_body(const bf16x8 (&qf)[2][DK / 32], const char* Ks, const char* Vs, SF& sf, FF& ff, POST& post,
;                          int cur, int c0, int c1, float (&m)[2], float (&l)[2], f32x4 (&o)[5][2], int fr, int fq) {
;     ...
;       if (MODE == 2) {
;         const float c = cl - m[rb];
; #pragma unroll
;         for (int kb = 0; kb < 4; ++kb)
; #pragma unroll
;           for (int j = 0; j < 4; ++j) {
;             const float e = FF::HASVEC ? opq(s[kb][rb][j] + c) : opq(fmaf(s[kb][rb][j], fsc, c));
;             s[kb][rb][j] = opq(fexp2(e) * l[rb]);
;           }
.LBB0_864:
	s_andn2_saveexec_b64 s[38:39], s[54:55]
	s_cbranch_execz .LBB0_866
	v_fmamk_f32 v0, v64, 0x3e38aa3b, v200
	v_fmamk_f32 v64, v65, 0x3e38aa3b, v200
	v_exp_f32_e32 v0, v0
	s_nop 0
	v_exp_f32_e32 v64, v64
	v_mul_f32_e32 v68, v104, v0
	v_fmamk_f32 v0, v66, 0x3e38aa3b, v200
	v_mul_f32_e32 v69, v104, v64
	v_exp_f32_e32 v0, v0
	v_fmamk_f32 v64, v67, 0x3e38aa3b, v200
	v_mul_f32_e32 v70, v104, v0
	v_fmamk_f32 v0, v60, 0x3e38aa3b, v200
	v_fmamk_f32 v60, v61, 0x3e38aa3b, v200
	v_exp_f32_e32 v0, v0
	v_exp_f32_e32 v64, v64
	v_exp_f32_e32 v60, v60
	v_mul_f32_e32 v72, v104, v0
	v_fmamk_f32 v0, v62, 0x3e38aa3b, v200
	v_mul_f32_e32 v73, v104, v60
	v_exp_f32_e32 v0, v0
	v_fmamk_f32 v60, v63, 0x3e38aa3b, v200
	v_mul_f32_e32 v71, v104, v64
	v_mul_f32_e32 v74, v104, v0
	v_fmamk_f32 v0, v56, 0x3e38aa3b, v200
	v_fmamk_f32 v56, v57, 0x3e38aa3b, v200
	v_exp_f32_e32 v0, v0
	v_exp_f32_e32 v60, v60
	v_exp_f32_e32 v56, v56
	v_mul_f32_e32 v76, v104, v0
	v_fmamk_f32 v0, v58, 0x3e38aa3b, v200
	v_mul_f32_e32 v77, v104, v56
	v_exp_f32_e32 v0, v0
	v_fmamk_f32 v56, v59, 0x3e38aa3b, v200
	v_mul_f32_e32 v75, v104, v60
	v_mul_f32_e32 v78, v104, v0
	v_fmamk_f32 v0, v52, 0x3e38aa3b, v200
	v_fmamk_f32 v52, v53, 0x3e38aa3b, v200
	v_exp_f32_e32 v56, v56
	v_exp_f32_e32 v0, v0
	v_exp_f32_e32 v52, v52
	v_mul_f32_e32 v79, v104, v56
	v_mul_f32_e32 v80, v104, v0
	v_mul_f32_e32 v81, v104, v52
	v_fmamk_f32 v0, v54, 0x3e38aa3b, v200
	v_fmamk_f32 v52, v55, 0x3e38aa3b, v200
	v_exp_f32_e32 v0, v0
	v_exp_f32_e32 v52, v52
	v_mul_f32_e32 v82, v104, v0
	v_mul_f32_e32 v83, v104, v52

; DEVI float opq(float x) { asm("" : "+v"(x)); return x; }
; DEVI float fexp2(float x) { return __builtin_amdgcn_exp2f(x); }
; template <int DK, int MODE, int RBM, class SF, class FF, class POST>
; DEVI void attn_tile_body(const bf16x8 (&qf)[2][DK / 32], const char* Ks, const char* Vs, SF& sf, FF& ff, POST& post,
;                          int cur, int c0, int c1, float (&m)[2], float (&l)[2], f32x4 (&o)[5][2], int fr, int fq) {
;     ...
;       if (MODE == 2) {
;         const float c = cl - m[rb];
; #pragma unroll
;         for (int kb = 0; kb < 4; ++kb)
; #pragma unroll
;           for (int j = 0; j < 4; ++j) {
;             const float e = FF::HASVEC ? opq(s[kb][rb][j] + c) : opq(fmaf(s[kb][rb][j], fsc, c));
;             s[kb][rb][j] = opq(fexp2(e) * l[rb]);
;           }
.LBB0_928:
	s_andn2_saveexec_b64 s[36:37], s[54:55]
	s_cbranch_execz .LBB0_930
	v_fmamk_f32 v76, v76, 0x3e38aa3b, v199
	v_fmamk_f32 v77, v77, 0x3e38aa3b, v199
	v_fmamk_f32 v72, v72, 0x3e38aa3b, v199
	v_fmamk_f32 v73, v73, 0x3e38aa3b, v199
	v_fmamk_f32 v68, v68, 0x3e38aa3b, v199
	v_fmamk_f32 v69, v69, 0x3e38aa3b, v199
	v_exp_f32_e32 v76, v76
	v_exp_f32_e32 v77, v77
	v_exp_f32_e32 v72, v72
	v_exp_f32_e32 v73, v73
	v_exp_f32_e32 v68, v68
	v_exp_f32_e32 v69, v69
	v_fmamk_f32 v2, v80, 0x3e38aa3b, v199
	v_fmamk_f32 v3, v81, 0x3e38aa3b, v199
	v_fmamk_f32 v80, v82, 0x3e38aa3b, v199
	v_fmamk_f32 v81, v83, 0x3e38aa3b, v199
	v_mul_f32_e32 v118, v102, v76
	v_mul_f32_e32 v119, v102, v77
	v_fmamk_f32 v76, v78, 0x3e38aa3b, v199
	v_fmamk_f32 v77, v79, 0x3e38aa3b, v199
	v_mul_f32_e32 v126, v102, v72
	v_mul_f32_e32 v127, v102, v73
	v_fmamk_f32 v72, v74, 0x3e38aa3b, v199
	v_fmamk_f32 v73, v75, 0x3e38aa3b, v199
	v_mul_f32_e32 v130, v102, v68
	v_mul_f32_e32 v131, v102, v69
	v_fmamk_f32 v68, v70, 0x3e38aa3b, v199
	v_fmamk_f32 v69, v71, 0x3e38aa3b, v199
	v_exp_f32_e32 v2, v2
	v_exp_f32_e32 v3, v3
	v_exp_f32_e32 v80, v80
	v_exp_f32_e32 v81, v81
	v_exp_f32_e32 v76, v76
	v_exp_f32_e32 v77, v77
	v_exp_f32_e32 v72, v72
	v_exp_f32_e32 v73, v73
	v_exp_f32_e32 v68, v68
	v_exp_f32_e32 v69, v69
	v_mul_f32_e32 v2, v102, v2
	v_mul_f32_e32 v3, v102, v3
	v_mul_f32_e32 v100, v102, v80
	v_mul_f32_e32 v101, v102, v81
	v_mul_f32_e32 v120, v102, v76
	v_mul_f32_e32 v121, v102, v77
	v_mul_f32_e32 v128, v102, v72
	v_mul_f32_e32 v129, v102, v73
	v_mul_f32_e32 v132, v102, v68
	v_mul_f32_e32 v133, v102, v69

; DEVI float opq(float x) { asm("" : "+v"(x)); return x; }
; DEVI float fexp2(float x) { return __builtin_amdgcn_exp2f(x); }
; template <int DK, int MODE, int RBM, class SF, class FF, class POST>
; DEVI void attn_tile_body(const bf16x8 (&qf)[2][DK / 32], const char* Ks, const char* Vs, SF& sf, FF& ff, POST& post,
;                          int cur, int c0, int c1, float (&m)[2], float (&l)[2], f32x4 (&o)[5][2], int fr, int fq) {
;     ...
;       if (MODE == 2) {
;         const float c = cl - m[rb];
; #pragma unroll
;         for (int kb = 0; kb < 4; ++kb)
; #pragma unroll
;           for (int j = 0; j < 4; ++j) {
;             const float e = FF::HASVEC ? opq(s[kb][rb][j] + c) : opq(fmaf(s[kb][rb][j], fsc, c));
;             s[kb][rb][j] = opq(fexp2(e) * l[rb]);
;           }
.LBB0_964:
	s_andn2_saveexec_b64 s[36:37], s[54:55]
	s_cbranch_execz .LBB0_966
	v_fmamk_f32 v0, v64, 0x3e38aa3b, v200
	v_fmamk_f32 v64, v65, 0x3e38aa3b, v200
	v_exp_f32_e32 v0, v0
	s_nop 0
	v_exp_f32_e32 v64, v64
	v_mul_f32_e32 v68, v104, v0
	v_fmamk_f32 v0, v66, 0x3e38aa3b, v200
	v_mul_f32_e32 v69, v104, v64
	v_exp_f32_e32 v0, v0
	v_fmamk_f32 v64, v67, 0x3e38aa3b, v200
	v_mul_f32_e32 v70, v104, v0
	v_fmamk_f32 v0, v60, 0x3e38aa3b, v200
	v_fmamk_f32 v60, v61, 0x3e38aa3b, v200
	v_exp_f32_e32 v0, v0
	v_exp_f32_e32 v64, v64
	v_exp_f32_e32 v60, v60
	v_mul_f32_e32 v72, v104, v0
	v_fmamk_f32 v0, v62, 0x3e38aa3b, v200
	v_mul_f32_e32 v73, v104, v60
	v_exp_f32_e32 v0, v0
	v_fmamk_f32 v60, v63, 0x3e38aa3b, v200
	v_mul_f32_e32 v71, v104, v64
	v_mul_f32_e32 v74, v104, v0
	v_fmamk_f32 v0, v56, 0x3e38aa3b, v200
	v_fmamk_f32 v56, v57, 0x3e38aa3b, v200
	v_exp_f32_e32 v0, v0
	v_exp_f32_e32 v60, v60
	v_exp_f32_e32 v56, v56
	v_mul_f32_e32 v76, v104, v0
	v_fmamk_f32 v0, v58, 0x3e38aa3b, v200
	v_mul_f32_e32 v77, v104, v56
	v_exp_f32_e32 v0, v0
	v_fmamk_f32 v56, v59, 0x3e38aa3b, v200
	v_mul_f32_e32 v75, v104, v60
	v_mul_f32_e32 v78, v104, v0
	v_fmamk_f32 v0, v52, 0x3e38aa3b, v200
	v_fmamk_f32 v52, v53, 0x3e38aa3b, v200
	v_exp_f32_e32 v56, v56
	v_exp_f32_e32 v0, v0
	v_exp_f32_e32 v52, v52
	v_mul_f32_e32 v79, v104, v56
	v_mul_f32_e32 v80, v104, v0
	v_mul_f32_e32 v81, v104, v52
	v_fmamk_f32 v0, v54, 0x3e38aa3b, v200
	v_fmamk_f32 v52, v55, 0x3e38aa3b, v200
	v_exp_f32_e32 v0, v0
	v_exp_f32_e32 v52, v52
	v_mul_f32_e32 v82, v104, v0
	v_mul_f32_e32 v83, v104, v52

; DEVI float opq(float x) { asm("" : "+v"(x)); return x; }
; DEVI float fexp2(float x) { return __builtin_amdgcn_exp2f(x); }
; template <int DK, int MODE, int RBM, class SF, class FF, class POST>
; DEVI void attn_tile_body(const bf16x8 (&qf)[2][DK / 32], const char* Ks, const char* Vs, SF& sf, FF& ff, POST& post,
;                          int cur, int c0, int c1, float (&m)[2], float (&l)[2], f32x4 (&o)[5][2], int fr, int fq) {
;     ...
;         const float c = cl - m[rb];
; #pragma unroll
;         for (int kb = 0; kb < 4; ++kb)
; #pragma unroll
;           for (int j = 0; j < 4; ++j) {
;             const float e = FF::HASVEC ? opq(s[kb][rb][j] + c) : opq(fmaf(s[kb][rb][j], fsc, c));
;             s[kb][rb][j] = fexp2(e);
.LBB0_1058:
	v_sub_f32_e32 v221, v126, v207
	v_fmamk_f32 v72, v72, 0x3e38aa3b, v221
	v_fmamk_f32 v68, v68, 0x3e38aa3b, v221
	v_fmamk_f32 v64, v64, 0x3e38aa3b, v221
	v_fmamk_f32 v60, v60, 0x3e38aa3b, v221
	v_exp_f32_e32 v213, v72
	v_fmamk_f32 v72, v73, 0x3e38aa3b, v221
	v_exp_f32_e32 v217, v68
	v_fmamk_f32 v68, v69, 0x3e38aa3b, v221
	v_exp_f32_e32 v222, v64
	v_fmamk_f32 v64, v65, 0x3e38aa3b, v221
	v_exp_f32_e32 v214, v72
	v_fmamk_f32 v72, v74, 0x3e38aa3b, v221
	v_exp_f32_e32 v218, v68
	v_fmamk_f32 v68, v70, 0x3e38aa3b, v221
	v_exp_f32_e32 v223, v64
	v_fmamk_f32 v64, v66, 0x3e38aa3b, v221
	v_exp_f32_e32 v226, v60
	v_fmamk_f32 v60, v61, 0x3e38aa3b, v221
	v_exp_f32_e32 v215, v72
	v_fmamk_f32 v72, v75, 0x3e38aa3b, v221
	v_exp_f32_e32 v219, v68
	v_fmamk_f32 v68, v71, 0x3e38aa3b, v221
	v_exp_f32_e32 v224, v64
	v_fmamk_f32 v64, v67, 0x3e38aa3b, v221
	v_exp_f32_e32 v227, v60
	v_fmamk_f32 v60, v62, 0x3e38aa3b, v221
	v_fmac_f32_e32 v221, 0x3e38aa3b, v63
	v_exp_f32_e32 v216, v72
	v_exp_f32_e32 v220, v68
	v_exp_f32_e32 v225, v64
	v_exp_f32_e32 v228, v60

; DEVI float opq(float x) { asm("" : "+v"(x)); return x; }
; DEVI float fexp2(float x) { return __builtin_amdgcn_exp2f(x); }
; template <int DK, int MODE, int RBM, class SF, class FF, class POST>
; DEVI void attn_tile_body(const bf16x8 (&qf)[2][DK / 32], const char* Ks, const char* Vs, SF& sf, FF& ff, POST& post,
;                          int cur, int c0, int c1, float (&m)[2], float (&l)[2], f32x4 (&o)[5][2], int fr, int fq) {
;     ...
;         const float c = cl - m[rb];
; #pragma unroll
;         for (int kb = 0; kb < 4; ++kb)
; #pragma unroll
;           for (int j = 0; j < 4; ++j) {
;             const float e = FF::HASVEC ? opq(s[kb][rb][j] + c) : opq(fmaf(s[kb][rb][j], fsc, c));
;             s[kb][rb][j] = fexp2(e);
.LBB0_1100:
	v_sub_f32_e32 v217, v2, v208
	v_fmamk_f32 v2, v72, 0x3e38aa3b, v217
	v_exp_f32_e32 v126, v2
	v_fmamk_f32 v2, v73, 0x3e38aa3b, v217
	v_exp_f32_e32 v127, v2
	v_fmamk_f32 v2, v74, 0x3e38aa3b, v217
	v_exp_f32_e32 v211, v2
	v_fmamk_f32 v2, v75, 0x3e38aa3b, v217
	v_exp_f32_e32 v212, v2
	v_fmamk_f32 v2, v68, 0x3e38aa3b, v217
	v_exp_f32_e32 v213, v2
	v_fmamk_f32 v2, v69, 0x3e38aa3b, v217
	v_exp_f32_e32 v214, v2
	v_fmamk_f32 v2, v70, 0x3e38aa3b, v217
	v_exp_f32_e32 v215, v2
	v_fmamk_f32 v2, v71, 0x3e38aa3b, v217
	v_exp_f32_e32 v216, v2
	v_fmamk_f32 v2, v64, 0x3e38aa3b, v217
	v_exp_f32_e32 v218, v2
	v_fmamk_f32 v2, v65, 0x3e38aa3b, v217
	v_exp_f32_e32 v219, v2
	v_fmamk_f32 v2, v66, 0x3e38aa3b, v217
	v_exp_f32_e32 v220, v2
	v_fmamk_f32 v2, v67, 0x3e38aa3b, v217
	v_exp_f32_e32 v221, v2
	v_fmamk_f32 v2, v60, 0x3e38aa3b, v217
	v_exp_f32_e32 v222, v2
	v_fmamk_f32 v2, v61, 0x3e38aa3b, v217
	v_exp_f32_e32 v223, v2
	v_fmamk_f32 v2, v62, 0x3e38aa3b, v217
	v_fmac_f32_e32 v217, 0x3e38aa3b, v63
	v_exp_f32_e32 v224, v2

; DEVI float opq(float x) { asm("" : "+v"(x)); return x; }
; DEVI float fexp2(float x) { return __builtin_amdgcn_exp2f(x); }
; template <int DK, int MODE, int RBM, class SF, class FF, class POST>
; DEVI void attn_tile_body(const bf16x8 (&qf)[2][DK / 32], const char* Ks, const char* Vs, SF& sf, FF& ff, POST& post,
;                          int cur, int c0, int c1, float (&m)[2], float (&l)[2], f32x4 (&o)[5][2], int fr, int fq) {
;     ...
;         const float c = cl - m[rb];
; #pragma unroll
;         for (int kb = 0; kb < 4; ++kb)
; #pragma unroll
;           for (int j = 0; j < 4; ++j) {
;             const float e = FF::HASVEC ? opq(s[kb][rb][j] + c) : opq(fmaf(s[kb][rb][j], fsc, c));
;             s[kb][rb][j] = fexp2(e);
.LBB0_1144:
	v_sub_f32_e32 v219, v126, v207
	v_fmamk_f32 v72, v72, 0x3e38aa3b, v219
	v_fmamk_f32 v68, v68, 0x3e38aa3b, v219
	v_fmamk_f32 v64, v64, 0x3e38aa3b, v219
	v_fmamk_f32 v60, v60, 0x3e38aa3b, v219
	v_exp_f32_e32 v211, v72
	v_fmamk_f32 v72, v73, 0x3e38aa3b, v219
	v_exp_f32_e32 v215, v68
	v_fmamk_f32 v68, v69, 0x3e38aa3b, v219
	v_exp_f32_e32 v220, v64
	v_fmamk_f32 v64, v65, 0x3e38aa3b, v219
	v_exp_f32_e32 v212, v72
	v_fmamk_f32 v72, v74, 0x3e38aa3b, v219
	v_exp_f32_e32 v216, v68
	v_fmamk_f32 v68, v70, 0x3e38aa3b, v219
	v_exp_f32_e32 v221, v64
	v_fmamk_f32 v64, v66, 0x3e38aa3b, v219
	v_exp_f32_e32 v224, v60
	v_fmamk_f32 v60, v61, 0x3e38aa3b, v219
	v_exp_f32_e32 v213, v72
	v_fmamk_f32 v72, v75, 0x3e38aa3b, v219
	v_exp_f32_e32 v217, v68
	v_fmamk_f32 v68, v71, 0x3e38aa3b, v219
	v_exp_f32_e32 v222, v64
	v_fmamk_f32 v64, v67, 0x3e38aa3b, v219
	v_exp_f32_e32 v225, v60
	v_fmamk_f32 v60, v62, 0x3e38aa3b, v219
	v_fmac_f32_e32 v219, 0x3e38aa3b, v63
	v_exp_f32_e32 v214, v72
	v_exp_f32_e32 v218, v68
	v_exp_f32_e32 v223, v64
	v_exp_f32_e32 v226, v60

; DEVI float opq(float x) { asm("" : "+v"(x)); return x; }
; DEVI float fexp2(float x) { return __builtin_amdgcn_exp2f(x); }
; template <int DK, int MODE, int RBM, class SF, class FF, class POST>
; DEVI void attn_tile_body(const bf16x8 (&qf)[2][DK / 32], const char* Ks, const char* Vs, SF& sf, FF& ff, POST& post,
;                          int cur, int c0, int c1, float (&m)[2], float (&l)[2], f32x4 (&o)[5][2], int fr, int fq) {
;     ...
;         const float c = cl - m[rb];
; #pragma unroll
;         for (int kb = 0; kb < 4; ++kb)
; #pragma unroll
;           for (int j = 0; j < 4; ++j) {
;             const float e = FF::HASVEC ? opq(s[kb][rb][j] + c) : opq(fmaf(s[kb][rb][j], fsc, c));
;             s[kb][rb][j] = fexp2(e);
.LBB0_1186:
	v_sub_f32_e32 v215, v0, v208
	v_fmamk_f32 v2, v74, 0x3e38aa3b, v215
	v_fmamk_f32 v0, v72, 0x3e38aa3b, v215
	v_exp_f32_e32 v127, v2
	v_fmamk_f32 v2, v75, 0x3e38aa3b, v215
	v_exp_f32_e32 v210, v2
	v_fmamk_f32 v2, v68, 0x3e38aa3b, v215
	v_exp_f32_e32 v126, v0
	v_exp_f32_e32 v211, v2
	v_fmamk_f32 v2, v69, 0x3e38aa3b, v215
	v_fmamk_f32 v0, v73, 0x3e38aa3b, v215
	v_exp_f32_e32 v212, v2
	v_fmamk_f32 v2, v70, 0x3e38aa3b, v215
	v_exp_f32_e32 v213, v2
	v_fmamk_f32 v2, v71, 0x3e38aa3b, v215
	v_exp_f32_e32 v0, v0
	v_exp_f32_e32 v214, v2
	v_fmamk_f32 v2, v64, 0x3e38aa3b, v215
	v_exp_f32_e32 v216, v2
	v_fmamk_f32 v2, v65, 0x3e38aa3b, v215
	v_exp_f32_e32 v217, v2
	v_fmamk_f32 v2, v66, 0x3e38aa3b, v215
	v_exp_f32_e32 v218, v2
	v_fmamk_f32 v2, v67, 0x3e38aa3b, v215
	v_exp_f32_e32 v219, v2
	v_fmamk_f32 v2, v60, 0x3e38aa3b, v215
	v_exp_f32_e32 v220, v2
	v_fmamk_f32 v2, v61, 0x3e38aa3b, v215
	v_exp_f32_e32 v221, v2
	v_fmamk_f32 v2, v62, 0x3e38aa3b, v215
	v_fmac_f32_e32 v215, 0x3e38aa3b, v63
	v_exp_f32_e32 v222, v2

; DEVI float opq(float x) { asm("" : "+v"(x)); return x; }
; DEVI float fexp2(float x) { return __builtin_amdgcn_exp2f(x); }
; template <int DK, int MODE, int RBM, class SF, class FF, class POST>
; DEVI void attn_tile_body(const bf16x8 (&qf)[2][DK / 32], const char* Ks, const char* Vs, SF& sf, FF& ff, POST& post,
;                          int cur, int c0, int c1, float (&m)[2], float (&l)[2], f32x4 (&o)[5][2], int fr, int fq) {
;     ...
;         const float c = cl - m[rb];
; #pragma unroll
;         for (int kb = 0; kb < 4; ++kb)
; #pragma unroll
;           for (int j = 0; j < 4; ++j) {
;             const float e = FF::HASVEC ? opq(s[kb][rb][j] + c) : opq(fmaf(s[kb][rb][j], fsc, c));
;             s[kb][rb][j] = fexp2(e);
.LBB0_1200:
	v_sub_f32_e32 v85, v136, v3
	v_fmamk_f32 v72, v72, 0x3e38aa3b, v85
	v_fmamk_f32 v68, v68, 0x3e38aa3b, v85
	v_fmamk_f32 v64, v64, 0x3e38aa3b, v85
	v_fmamk_f32 v60, v60, 0x3e38aa3b, v85
	v_exp_f32_e32 v77, v72
	v_fmamk_f32 v72, v73, 0x3e38aa3b, v85
	v_exp_f32_e32 v80, v68
	v_fmamk_f32 v68, v69, 0x3e38aa3b, v85
	v_exp_f32_e32 v83, v64
	v_fmamk_f32 v64, v65, 0x3e38aa3b, v85
	v_exp_f32_e32 v76, v72
	v_fmamk_f32 v72, v74, 0x3e38aa3b, v85
	v_exp_f32_e32 v81, v68
	v_fmamk_f32 v68, v70, 0x3e38aa3b, v85
	v_exp_f32_e32 v86, v64
	v_fmamk_f32 v64, v66, 0x3e38aa3b, v85
	v_exp_f32_e32 v89, v60
	v_fmamk_f32 v60, v61, 0x3e38aa3b, v85
	v_exp_f32_e32 v78, v72
	v_fmamk_f32 v72, v75, 0x3e38aa3b, v85
	v_exp_f32_e32 v82, v68
	v_fmamk_f32 v68, v71, 0x3e38aa3b, v85
	v_exp_f32_e32 v87, v64
	v_fmamk_f32 v64, v67, 0x3e38aa3b, v85
	v_exp_f32_e32 v90, v60
	v_fmamk_f32 v60, v62, 0x3e38aa3b, v85
	v_fmac_f32_e32 v85, 0x3e38aa3b, v63
	v_exp_f32_e32 v79, v72
	v_exp_f32_e32 v84, v68
	v_exp_f32_e32 v88, v64
	v_exp_f32_e32 v91, v60

; DEVI float opq(float x) { asm("" : "+v"(x)); return x; }
; DEVI float fexp2(float x) { return __builtin_amdgcn_exp2f(x); }
; template <int DK, int MODE, int RBM, class SF, class FF, class POST>
; DEVI void attn_tile_body(const bf16x8 (&qf)[2][DK / 32], const char* Ks, const char* Vs, SF& sf, FF& ff, POST& post,
;                          int cur, int c0, int c1, float (&m)[2], float (&l)[2], f32x4 (&o)[5][2], int fr, int fq) {
;     ...
;         const float c = cl - m[rb];
; #pragma unroll
;         for (int kb = 0; kb < 4; ++kb)
; #pragma unroll
;           for (int j = 0; j < 4; ++j) {
;             const float e = FF::HASVEC ? opq(s[kb][rb][j] + c) : opq(fmaf(s[kb][rb][j], fsc, c));
;             s[kb][rb][j] = fexp2(e);
.LBB0_1248:
	v_sub_f32_e32 v221, v136, v211
	v_fmamk_f32 v88, v88, 0x3e38aa3b, v221
	v_fmamk_f32 v84, v84, 0x3e38aa3b, v221
	v_fmamk_f32 v80, v80, 0x3e38aa3b, v221
	v_fmamk_f32 v76, v76, 0x3e38aa3b, v221
	v_exp_f32_e32 v214, v88
	v_fmamk_f32 v88, v89, 0x3e38aa3b, v221
	v_exp_f32_e32 v218, v84
	v_fmamk_f32 v84, v85, 0x3e38aa3b, v221
	v_exp_f32_e32 v222, v80
	v_fmamk_f32 v80, v81, 0x3e38aa3b, v221
	v_exp_f32_e32 v215, v88
	v_fmamk_f32 v88, v90, 0x3e38aa3b, v221
	v_exp_f32_e32 v219, v84
	v_fmamk_f32 v84, v86, 0x3e38aa3b, v221
	v_exp_f32_e32 v224, v80
	v_fmamk_f32 v80, v82, 0x3e38aa3b, v221
	v_exp_f32_e32 v227, v76
	v_fmamk_f32 v76, v77, 0x3e38aa3b, v221
	v_exp_f32_e32 v216, v88
	v_fmamk_f32 v88, v91, 0x3e38aa3b, v221
	v_exp_f32_e32 v220, v84
	v_fmamk_f32 v84, v87, 0x3e38aa3b, v221
	v_exp_f32_e32 v225, v80
	v_fmamk_f32 v80, v83, 0x3e38aa3b, v221
	v_exp_f32_e32 v228, v76
	v_fmamk_f32 v76, v78, 0x3e38aa3b, v221
	v_fmac_f32_e32 v221, 0x3e38aa3b, v79
	v_exp_f32_e32 v217, v88
	v_exp_f32_e32 v223, v84
	v_exp_f32_e32 v226, v80
	v_exp_f32_e32 v229, v76

; DEVI float opq(float x) { asm("" : "+v"(x)); return x; }
; DEVI float fexp2(float x) { return __builtin_amdgcn_exp2f(x); }
; template <int DK, int MODE, int RBM, class SF, class FF, class POST>
; DEVI void attn_tile_body(const bf16x8 (&qf)[2][DK / 32], const char* Ks, const char* Vs, SF& sf, FF& ff, POST& post,
;                          int cur, int c0, int c1, float (&m)[2], float (&l)[2], f32x4 (&o)[5][2], int fr, int fq) {
;     ...
;         const float c = cl - m[rb];
; #pragma unroll
;         for (int kb = 0; kb < 4; ++kb)
; #pragma unroll
;           for (int j = 0; j < 4; ++j) {
;             const float e = FF::HASVEC ? opq(s[kb][rb][j] + c) : opq(fmaf(s[kb][rb][j], fsc, c));
;             s[kb][rb][j] = fexp2(e);
.LBB0_1331:
	v_sub_f32_e32 v220, v136, v211
	v_fmamk_f32 v88, v88, 0x3e38aa3b, v220
	v_fmamk_f32 v84, v84, 0x3e38aa3b, v220
	v_fmamk_f32 v80, v80, 0x3e38aa3b, v220
	v_fmamk_f32 v76, v76, 0x3e38aa3b, v220
	v_exp_f32_e32 v213, v88
	v_fmamk_f32 v88, v89, 0x3e38aa3b, v220
	v_exp_f32_e32 v217, v84
	v_fmamk_f32 v84, v85, 0x3e38aa3b, v220
	v_exp_f32_e32 v221, v80
	v_fmamk_f32 v80, v81, 0x3e38aa3b, v220
	v_exp_f32_e32 v214, v88
	v_fmamk_f32 v88, v90, 0x3e38aa3b, v220
	v_exp_f32_e32 v218, v84
	v_fmamk_f32 v84, v86, 0x3e38aa3b, v220
	v_exp_f32_e32 v223, v80
	v_fmamk_f32 v80, v82, 0x3e38aa3b, v220
	v_exp_f32_e32 v226, v76
	v_fmamk_f32 v76, v77, 0x3e38aa3b, v220
	v_exp_f32_e32 v215, v88
	v_fmamk_f32 v88, v91, 0x3e38aa3b, v220
	v_exp_f32_e32 v219, v84
	v_fmamk_f32 v84, v87, 0x3e38aa3b, v220
	v_exp_f32_e32 v224, v80
	v_fmamk_f32 v80, v83, 0x3e38aa3b, v220
	v_exp_f32_e32 v227, v76
	v_fmamk_f32 v76, v78, 0x3e38aa3b, v220
	v_fmac_f32_e32 v220, 0x3e38aa3b, v79
	v_exp_f32_e32 v216, v88
	v_exp_f32_e32 v222, v84
	v_exp_f32_e32 v225, v80
	v_exp_f32_e32 v228, v76
